# placement: FFN-F2 epilogue shifted 8 bytes relative to its main loop (loop head stays at 40 mod 64)
# baseline (speedup 1.0000x reference)
.LBB0_1057:
	s_add_u32 s12, s0, 0xfff80080
	s_addc_u32 s13, s1, -1
	s_add_i32 s50, 0, 0x10000
	s_cmp_eq_u32 s33, 28
	s_cselect_b32 s15, s20, s13
	s_cselect_b32 s14, s21, s12
	s_cselect_b32 s13, s22, s27
	s_cselect_b32 s12, s23, s26
	s_add_i32 s53, 0, 0x14000
	ds_read_b128 v[88:91], v253
	ds_read_b128 v[92:95], v253 offset:1024
	ds_read_b128 v[96:99], v253 offset:2048
	ds_read_b128 v[100:103], v253 offset:3072
	ds_read_b128 v[108:111], v253 offset:16384
	ds_read_b128 v[112:115], v253 offset:17408
	ds_read_b128 v[116:119], v253 offset:18432
	ds_read_b128 v[120:123], v253 offset:19456
	s_add_i32 m0, s42, 0xc000
	ds_read_b128 v[152:155], v224
	ds_read_b128 v[164:167], v224 offset:1024
	ds_read_b128 v[168:171], v224 offset:2048
	ds_read_b128 v[172:175], v224 offset:3072
	ds_read_b128 v[188:191], v224 offset:4096
	ds_read_b128 v[192:195], v224 offset:5120
	ds_read_b128 v[196:199], v224 offset:6144
	ds_read_b128 v[200:203], v224 offset:7168
	global_load_lds_dwordx4 v184, s[0:1]
	s_add_i32 m0, s42, 0xe000
	s_nop 0
	global_load_lds_dwordx4 v186, s[0:1]
	s_waitcnt vmcnt(8)
	s_waitcnt lgkmcnt(0)
	s_barrier
	s_setprio 1
	s_waitcnt lgkmcnt(0)
	v_mfma_f32_16x16x32_bf16 v[160:163], v[88:91], v[152:155], v[160:163]
	v_mfma_f32_16x16x32_bf16 v[156:159], v[96:99], v[152:155], v[156:159]
	v_mfma_f32_16x16x32_bf16 v[148:151], v[88:91], v[168:171], v[148:151]
	v_mfma_f32_16x16x32_bf16 v[144:147], v[96:99], v[168:171], v[144:147]
	v_mfma_f32_16x16x32_bf16 v[140:143], v[88:91], v[188:191], v[140:143]
	v_mfma_f32_16x16x32_bf16 v[136:139], v[96:99], v[188:191], v[136:139]
	v_mfma_f32_16x16x32_bf16 v[132:135], v[88:91], v[196:199], v[132:135]
	v_mfma_f32_16x16x32_bf16 v[128:131], v[96:99], v[196:199], v[128:131]
	v_mfma_f32_16x16x32_bf16 v[160:163], v[92:95], v[164:167], v[160:163]
	v_mfma_f32_16x16x32_bf16 v[156:159], v[100:103], v[164:167], v[156:159]
	v_mfma_f32_16x16x32_bf16 v[148:151], v[92:95], v[172:175], v[148:151]
	v_mfma_f32_16x16x32_bf16 v[144:147], v[100:103], v[172:175], v[144:147]
	v_mfma_f32_16x16x32_bf16 v[140:143], v[92:95], v[192:195], v[140:143]
	v_mfma_f32_16x16x32_bf16 v[136:139], v[100:103], v[192:195], v[136:139]
	v_mfma_f32_16x16x32_bf16 v[132:135], v[92:95], v[200:203], v[132:135]
	v_mfma_f32_16x16x32_bf16 v[128:131], v[100:103], v[200:203], v[128:131]
	s_setprio 0
	s_setprio 1
	v_mfma_f32_16x16x32_bf16 v[60:63], v[108:111], v[152:155], v[60:63]
	v_mfma_f32_16x16x32_bf16 v[56:59], v[116:119], v[152:155], v[56:59]
	v_mfma_f32_16x16x32_bf16 v[52:55], v[108:111], v[168:171], v[52:55]
	v_mfma_f32_16x16x32_bf16 v[48:51], v[116:119], v[168:171], v[48:51]
	v_mfma_f32_16x16x32_bf16 v[44:47], v[108:111], v[188:191], v[44:47]
	v_mfma_f32_16x16x32_bf16 v[40:43], v[116:119], v[188:191], v[40:43]
	v_mfma_f32_16x16x32_bf16 v[36:39], v[108:111], v[196:199], v[36:39]
	v_mfma_f32_16x16x32_bf16 v[32:35], v[116:119], v[196:199], v[32:35]
	v_mfma_f32_16x16x32_bf16 v[60:63], v[112:115], v[164:167], v[60:63]
	v_mfma_f32_16x16x32_bf16 v[56:59], v[120:123], v[164:167], v[56:59]
	v_mfma_f32_16x16x32_bf16 v[52:55], v[112:115], v[172:175], v[52:55]
	v_mfma_f32_16x16x32_bf16 v[48:51], v[120:123], v[172:175], v[48:51]
	v_mfma_f32_16x16x32_bf16 v[44:47], v[112:115], v[192:195], v[44:47]
	v_mfma_f32_16x16x32_bf16 v[40:43], v[120:123], v[192:195], v[40:43]
	v_mfma_f32_16x16x32_bf16 v[36:39], v[112:115], v[200:203], v[36:39]
	v_mfma_f32_16x16x32_bf16 v[32:35], v[120:123], v[200:203], v[32:35]
	s_setprio 0
	s_barrier
	s_add_i32 s50, s50, s39
	s_mov_b32 m0, s50
	ds_read_b128 v[152:155], v224 offset:16384
	ds_read_b128 v[164:167], v224 offset:17408
	ds_read_b128 v[168:171], v224 offset:18432
	ds_read_b128 v[172:175], v224 offset:19456
	ds_read_b128 v[188:191], v224 offset:20480
	ds_read_b128 v[192:195], v224 offset:21504
	ds_read_b128 v[196:199], v224 offset:22528
	ds_read_b128 v[200:203], v224 offset:23552
	global_load_lds_dwordx4 v176, s[12:13]
	s_add_i32 m0, s50, 0x2000
	s_add_u32 s50, s12, 0x80000
	s_addc_u32 s51, s13, 0
	s_add_i32 s53, s53, s39
	global_load_lds_dwordx4 v178, s[12:13]
	s_mov_b32 m0, s53
	s_nop 0
	global_load_lds_dwordx4 v176, s[50:51]
	s_add_i32 m0, s53, 0x2000
	s_nop 0
	global_load_lds_dwordx4 v178, s[50:51]
	s_add_u32 s62, s14, 0x80
	s_addc_u32 s63, s15, 0
	s_mov_b32 m0, s42
	s_nop 0
	global_load_lds_dwordx4 v182, s[14:15]
	s_mov_b32 m0, s43
	s_nop 0
	global_load_lds_dwordx4 v180, s[14:15]
	s_waitcnt vmcnt(8)
	s_waitcnt lgkmcnt(0)
	s_barrier
	s_setprio 1
	s_waitcnt lgkmcnt(0)
	v_mfma_f32_16x16x32_bf16 v[124:127], v[88:91], v[152:155], v[124:127]
	v_mfma_f32_16x16x32_bf16 v[104:107], v[96:99], v[152:155], v[104:107]
	v_mfma_f32_16x16x32_bf16 v[84:87], v[88:91], v[168:171], v[84:87]
	v_mfma_f32_16x16x32_bf16 v[80:83], v[96:99], v[168:171], v[80:83]
	v_mfma_f32_16x16x32_bf16 v[76:79], v[88:91], v[188:191], v[76:79]
	v_mfma_f32_16x16x32_bf16 v[72:75], v[96:99], v[188:191], v[72:75]
	v_mfma_f32_16x16x32_bf16 v[68:71], v[88:91], v[196:199], v[68:71]
	v_mfma_f32_16x16x32_bf16 v[64:67], v[96:99], v[196:199], v[64:67]
	v_mfma_f32_16x16x32_bf16 v[124:127], v[92:95], v[164:167], v[124:127]
	v_mfma_f32_16x16x32_bf16 v[104:107], v[100:103], v[164:167], v[104:107]
	v_mfma_f32_16x16x32_bf16 v[84:87], v[92:95], v[172:175], v[84:87]
	v_mfma_f32_16x16x32_bf16 v[80:83], v[100:103], v[172:175], v[80:83]
	v_mfma_f32_16x16x32_bf16 v[76:79], v[92:95], v[192:195], v[76:79]
	v_mfma_f32_16x16x32_bf16 v[72:75], v[100:103], v[192:195], v[72:75]
	v_mfma_f32_16x16x32_bf16 v[68:71], v[92:95], v[200:203], v[68:71]
	v_mfma_f32_16x16x32_bf16 v[64:67], v[100:103], v[200:203], v[64:67]
	s_setprio 0
	s_setprio 1
	v_mfma_f32_16x16x32_bf16 v[28:31], v[108:111], v[152:155], v[28:31]
	v_mfma_f32_16x16x32_bf16 v[24:27], v[116:119], v[152:155], v[24:27]
	v_mfma_f32_16x16x32_bf16 v[20:23], v[108:111], v[168:171], v[20:23]
	v_mfma_f32_16x16x32_bf16 v[16:19], v[116:119], v[168:171], v[16:19]
	v_mfma_f32_16x16x32_bf16 v[12:15], v[108:111], v[188:191], v[12:15]
	v_mfma_f32_16x16x32_bf16 v[8:11], v[116:119], v[188:191], v[8:11]
	v_mfma_f32_16x16x32_bf16 v[4:7], v[108:111], v[196:199], v[4:7]
	v_mfma_f32_16x16x32_bf16 v[0:3], v[116:119], v[196:199], v[0:3]
	v_mfma_f32_16x16x32_bf16 v[28:31], v[112:115], v[164:167], v[28:31]
	v_mfma_f32_16x16x32_bf16 v[24:27], v[120:123], v[164:167], v[24:27]
	v_mfma_f32_16x16x32_bf16 v[20:23], v[112:115], v[172:175], v[20:23]
	v_mfma_f32_16x16x32_bf16 v[16:19], v[120:123], v[172:175], v[16:19]
	v_mfma_f32_16x16x32_bf16 v[12:15], v[112:115], v[192:195], v[12:15]
	v_mfma_f32_16x16x32_bf16 v[8:11], v[120:123], v[192:195], v[8:11]
	v_mfma_f32_16x16x32_bf16 v[4:7], v[112:115], v[200:203], v[4:7]
	v_mfma_f32_16x16x32_bf16 v[0:3], v[120:123], v[200:203], v[0:3]
	s_setprio 0
	s_barrier
	s_add_i32 s50, 0, 0x18000
	s_add_i32 s51, 0, 0x1c000
	ds_read_b128 v[88:91], v253 offset:32768
	ds_read_b128 v[92:95], v253 offset:33792
	ds_read_b128 v[96:99], v253 offset:34816
	ds_read_b128 v[100:103], v253 offset:35840
	ds_read_b128 v[108:111], v253 offset:49152
	ds_read_b128 v[112:115], v253 offset:50176
	ds_read_b128 v[116:119], v253 offset:51200
	ds_read_b128 v[120:123], v253 offset:52224
	s_add_u32 s14, s14, 0x80000
	s_addc_u32 s15, s15, 0
	s_mov_b32 m0, s44
	ds_read_b128 v[152:155], v224 offset:32768
	ds_read_b128 v[164:167], v224 offset:33792
	ds_read_b128 v[168:171], v224 offset:34816
	ds_read_b128 v[172:175], v224 offset:35840
	ds_read_b128 v[188:191], v224 offset:36864
	ds_read_b128 v[192:195], v224 offset:37888
	ds_read_b128 v[196:199], v224 offset:38912
	ds_read_b128 v[200:203], v224 offset:39936
	global_load_lds_dwordx4 v182, s[14:15]
	s_mov_b32 m0, s45
	s_nop 0
	global_load_lds_dwordx4 v180, s[14:15]
	s_waitcnt vmcnt(8)
	s_waitcnt lgkmcnt(0)
	s_barrier
	s_setprio 1
	s_waitcnt lgkmcnt(0)
	v_mfma_f32_16x16x32_bf16 v[160:163], v[88:91], v[152:155], v[160:163]
	v_mfma_f32_16x16x32_bf16 v[156:159], v[96:99], v[152:155], v[156:159]
	v_mfma_f32_16x16x32_bf16 v[148:151], v[88:91], v[168:171], v[148:151]
	v_mfma_f32_16x16x32_bf16 v[144:147], v[96:99], v[168:171], v[144:147]
	v_mfma_f32_16x16x32_bf16 v[140:143], v[88:91], v[188:191], v[140:143]
	v_mfma_f32_16x16x32_bf16 v[136:139], v[96:99], v[188:191], v[136:139]
	v_mfma_f32_16x16x32_bf16 v[132:135], v[88:91], v[196:199], v[132:135]
	v_mfma_f32_16x16x32_bf16 v[128:131], v[96:99], v[196:199], v[128:131]
	v_mfma_f32_16x16x32_bf16 v[160:163], v[92:95], v[164:167], v[160:163]
	v_mfma_f32_16x16x32_bf16 v[156:159], v[100:103], v[164:167], v[156:159]
	v_mfma_f32_16x16x32_bf16 v[148:151], v[92:95], v[172:175], v[148:151]
	v_mfma_f32_16x16x32_bf16 v[144:147], v[100:103], v[172:175], v[144:147]
	v_mfma_f32_16x16x32_bf16 v[140:143], v[92:95], v[192:195], v[140:143]
	v_mfma_f32_16x16x32_bf16 v[136:139], v[100:103], v[192:195], v[136:139]
	v_mfma_f32_16x16x32_bf16 v[132:135], v[92:95], v[200:203], v[132:135]
	v_mfma_f32_16x16x32_bf16 v[128:131], v[100:103], v[200:203], v[128:131]
	s_setprio 0
	s_setprio 1
	v_mfma_f32_16x16x32_bf16 v[60:63], v[108:111], v[152:155], v[60:63]
	v_mfma_f32_16x16x32_bf16 v[56:59], v[116:119], v[152:155], v[56:59]
	v_mfma_f32_16x16x32_bf16 v[52:55], v[108:111], v[168:171], v[52:55]
	v_mfma_f32_16x16x32_bf16 v[48:51], v[116:119], v[168:171], v[48:51]
	v_mfma_f32_16x16x32_bf16 v[44:47], v[108:111], v[188:191], v[44:47]
	v_mfma_f32_16x16x32_bf16 v[40:43], v[116:119], v[188:191], v[40:43]
	v_mfma_f32_16x16x32_bf16 v[36:39], v[108:111], v[196:199], v[36:39]
	v_mfma_f32_16x16x32_bf16 v[32:35], v[116:119], v[196:199], v[32:35]
	v_mfma_f32_16x16x32_bf16 v[60:63], v[112:115], v[164:167], v[60:63]
	v_mfma_f32_16x16x32_bf16 v[56:59], v[120:123], v[164:167], v[56:59]
	v_mfma_f32_16x16x32_bf16 v[52:55], v[112:115], v[172:175], v[52:55]
	v_mfma_f32_16x16x32_bf16 v[48:51], v[120:123], v[172:175], v[48:51]
	v_mfma_f32_16x16x32_bf16 v[44:47], v[112:115], v[192:195], v[44:47]
	v_mfma_f32_16x16x32_bf16 v[40:43], v[120:123], v[192:195], v[40:43]
	v_mfma_f32_16x16x32_bf16 v[36:39], v[112:115], v[200:203], v[36:39]
	v_mfma_f32_16x16x32_bf16 v[32:35], v[120:123], v[200:203], v[32:35]
	s_setprio 0
	s_barrier
	s_add_i32 s14, s50, s39
	s_mov_b32 m0, s14
	ds_read_b128 v[152:155], v224 offset:49152
	ds_read_b128 v[164:167], v224 offset:50176
	ds_read_b128 v[168:171], v224 offset:51200
	ds_read_b128 v[172:175], v224 offset:52224
	ds_read_b128 v[188:191], v224 offset:53248
	ds_read_b128 v[192:195], v224 offset:54272
	ds_read_b128 v[196:199], v224 offset:55296
	ds_read_b128 v[200:203], v224 offset:56320
	s_add_u32 s98, s12, 0x80
	s_addc_u32 s99, s13, 0
	global_load_lds_dwordx4 v176, s[98:99]
	s_add_i32 m0, s14, 0x2000
	s_add_u32 s12, s12, 0x80080
	s_addc_u32 s13, s13, 0
	s_add_i32 s14, s51, s39
	s_add_u32 s98, s12, 0xfff80000
	s_addc_u32 s99, s13, -1
	global_load_lds_dwordx4 v178, s[98:99]
	s_mov_b32 m0, s14
	s_nop 0
	global_load_lds_dwordx4 v176, s[12:13]
	s_add_i32 m0, s14, 0x2000
	s_nop 0
	global_load_lds_dwordx4 v178, s[12:13]
	s_mov_b32 m0, s61
	s_nop 0
	global_load_lds_dwordx4 v182, s[62:63]
	s_mov_b32 m0, s64
	s_nop 0
	global_load_lds_dwordx4 v180, s[62:63]
	s_waitcnt vmcnt(8)
	s_waitcnt lgkmcnt(0)
	s_barrier
	s_setprio 1
	s_waitcnt lgkmcnt(0)
	v_mfma_f32_16x16x32_bf16 v[124:127], v[88:91], v[152:155], v[124:127]
	v_mfma_f32_16x16x32_bf16 v[104:107], v[96:99], v[152:155], v[104:107]
	v_mfma_f32_16x16x32_bf16 v[84:87], v[88:91], v[168:171], v[84:87]
	v_mfma_f32_16x16x32_bf16 v[80:83], v[96:99], v[168:171], v[80:83]
	v_mfma_f32_16x16x32_bf16 v[76:79], v[88:91], v[188:191], v[76:79]
	v_mfma_f32_16x16x32_bf16 v[72:75], v[96:99], v[188:191], v[72:75]
	v_mfma_f32_16x16x32_bf16 v[68:71], v[88:91], v[196:199], v[68:71]
	v_mfma_f32_16x16x32_bf16 v[64:67], v[96:99], v[196:199], v[64:67]
	v_mfma_f32_16x16x32_bf16 v[124:127], v[92:95], v[164:167], v[124:127]
	v_mfma_f32_16x16x32_bf16 v[104:107], v[100:103], v[164:167], v[104:107]
	v_mfma_f32_16x16x32_bf16 v[84:87], v[92:95], v[172:175], v[84:87]
	v_mfma_f32_16x16x32_bf16 v[80:83], v[100:103], v[172:175], v[80:83]
	v_mfma_f32_16x16x32_bf16 v[76:79], v[92:95], v[192:195], v[76:79]
	v_mfma_f32_16x16x32_bf16 v[72:75], v[100:103], v[192:195], v[72:75]
	v_mfma_f32_16x16x32_bf16 v[68:71], v[92:95], v[200:203], v[68:71]
	v_mfma_f32_16x16x32_bf16 v[64:67], v[100:103], v[200:203], v[64:67]
	s_setprio 0
	s_setprio 1
	v_mfma_f32_16x16x32_bf16 v[28:31], v[108:111], v[152:155], v[28:31]
	v_mfma_f32_16x16x32_bf16 v[24:27], v[116:119], v[152:155], v[24:27]
	v_mfma_f32_16x16x32_bf16 v[20:23], v[108:111], v[168:171], v[20:23]
	v_mfma_f32_16x16x32_bf16 v[16:19], v[116:119], v[168:171], v[16:19]
	v_mfma_f32_16x16x32_bf16 v[12:15], v[108:111], v[188:191], v[12:15]
	v_mfma_f32_16x16x32_bf16 v[8:11], v[116:119], v[188:191], v[8:11]
	v_mfma_f32_16x16x32_bf16 v[4:7], v[108:111], v[196:199], v[4:7]
	v_mfma_f32_16x16x32_bf16 v[0:3], v[116:119], v[196:199], v[0:3]
	v_mfma_f32_16x16x32_bf16 v[28:31], v[112:115], v[164:167], v[28:31]
	v_mfma_f32_16x16x32_bf16 v[24:27], v[120:123], v[164:167], v[24:27]
	v_mfma_f32_16x16x32_bf16 v[20:23], v[112:115], v[172:175], v[20:23]
	v_mfma_f32_16x16x32_bf16 v[16:19], v[120:123], v[172:175], v[16:19]
	v_mfma_f32_16x16x32_bf16 v[12:15], v[112:115], v[192:195], v[12:15]
	v_mfma_f32_16x16x32_bf16 v[8:11], v[120:123], v[192:195], v[8:11]
	v_mfma_f32_16x16x32_bf16 v[4:7], v[112:115], v[200:203], v[4:7]
	v_mfma_f32_16x16x32_bf16 v[0:3], v[120:123], v[200:203], v[0:3]
	s_setprio 0
	s_barrier
	s_add_i32 s33, s33, 2
	s_add_u32 s0, s0, 0x100
	s_addc_u32 s1, s1, 0
	s_add_u32 s26, s26, 0x100
	s_addc_u32 s27, s27, 0
	s_cmp_gt_u32 s33, 29
	s_cbranch_scc0 .LBB0_1057
	s_nop 0
	s_nop 0
	s_and_b64 vcc, exec, s[40:41]
	s_cbranch_vccz .LBB0_1060
	s_barrier

.LBB0_1154:
	s_lshl_b32 s6, s20, 1
	s_or_b32 s13, s6, 1
	s_mul_i32 s7, s13, 0x3000
	s_mul_hi_u32 s6, s13, 0x3000
	s_add_u32 s7, s18, s7
	s_addc_u32 s6, s19, s6
	s_add_u32 s42, s7, 0x20000
	s_addc_u32 s43, s6, 0
	s_lshl_b32 s72, s20, 11
	s_lshl_b64 s[6:7], s[72:73], 2
	s_waitcnt lgkmcnt(0)
	s_add_u32 s36, s4, s6
	s_addc_u32 s37, s5, s7
	s_add_u32 s14, s18, 0x40000
	s_mul_i32 s4, s20, 0xc000
	s_addc_u32 s15, s19, 0
	s_add_i32 s6, s4, 0xc000
	s_and_b64 s[4:5], exec, s[8:9]
	s_cselect_b32 s72, 0, s6
	s_lshl_b64 s[4:5], s[72:73], 2
	s_add_u32 s6, s14, s4
	s_addc_u32 s7, s15, s5
	s_mul_hi_u32 s4, s13, 0x18000
	s_mul_i32 s13, s13, 0x18000
	s_add_u32 s40, s14, s13
	s_addc_u32 s41, s15, s4
	s_add_u32 s46, s18, 0x100000
	s_addc_u32 s47, s19, 0
	s_add_u32 s48, s18, 0x10200
	s_addc_u32 s49, s19, 0
	s_and_b32 s8, s3, 3
	s_lshl_b32 s3, s12, 6
	s_lshl_b32 s9, s12, 13
	s_lshl_b32 s13, s8, 12
	s_add_u32 s18, s18, 0x8800000
	s_addc_u32 s19, s19, 0
	s_add_i32 m0, s28, 0x18000
	v_lshl_add_u64 v[6:7], v[6:7], 0, s[74:75]
	s_waitcnt vmcnt(2)
	s_barrier
	global_load_lds_dwordx4 v[6:7], off
	v_lshl_add_u64 v[4:5], v[4:5], 0, s[74:75]
	s_add_i32 m0, s28, 0x1a000
	s_add_i32 s44, s28, 0x8000
	s_add_i32 s45, s28, 0xa000
	global_load_lds_dwordx4 v[4:5], off
	v_lshl_add_u64 v[0:1], v[0:1], 0, s[74:75]
	s_mov_b32 m0, s44
	s_add_u32 s4, s30, 0x160080
	global_load_lds_dwordx4 v[0:1], off
	v_lshl_add_u64 v[0:1], v[2:3], 0, s[74:75]
	s_mov_b32 m0, s45
	s_addc_u32 s5, s31, 0
	global_load_lds_dwordx4 v[0:1], off
	s_add_i32 m0, s28, 0x1c000
	v_lshl_add_u64 v[0:1], s[4:5], 0, v[176:177]
	global_load_lds_dwordx4 v[0:1], off
	v_lshl_add_u64 v[0:1], s[4:5], 0, v[182:183]
	s_add_i32 m0, s28, 0x1e000
	v_lshlrev_b32_e32 v5, 2, v15
	global_load_lds_dwordx4 v[0:1], off
	v_and_b32_e32 v0, 15, v15
	v_bfe_u32 v1, v15, 4, 2
	v_or_b32_e32 v184, s3, v0
	v_lshlrev_b32_e32 v2, 4, v1
	v_lshlrev_b32_e32 v3, 2, v184
	s_cmpk_lt_u32 s2, 0x100
	v_lshl_or_b32 v2, v0, 6, v2
	v_and_b32_e32 v4, 32, v3
	v_and_b32_e32 v5, 32, v5
	s_cselect_b64 s[52:53], -1, 0
	s_add_i32 s2, s3, 0x80
	v_bitop3_b32 v4, v2, s9, v4 bitop3:0xde
	v_bitop3_b32 v204, v2, s13, v5 bitop3:0xde
	v_lshlrev_b32_e32 v2, 4, v0
	v_ashrrev_i32_e32 v185, 31, v184
	v_or_b32_e32 v0, s2, v0
	s_ashr_i32 s2, s3, 31
	v_lshl_add_u64 v[186:187], v[184:185], 2, s[6:7]
	v_mov_b32_e32 v185, s2
	v_lshl_add_u64 v[188:189], v[184:185], 2, s[6:7]
	s_mov_b64 s[2:3], 0xc0
	v_lshl_add_u64 v[194:195], v[188:189], 0, s[2:3]
	s_lshl_b32 s2, s8, 2
	s_lshl_b32 s9, s12, 10
	s_add_i32 s2, s2, 0
	s_add_i32 s2, s2, s9
	s_add_i32 s6, s2, 0x20c00
	v_readlane_b32 s2, v254, 57
	s_movk_i32 s7, 0x1600
	v_lshlrev_b32_e32 v6, 3, v1
	v_cmp_eq_u32_e64 s[4:5], 0, v1
	v_lshl_add_u32 v209, v0, 2, s2
	v_lshrrev_b32_e32 v1, 1, v8
	v_mul_lo_u32 v0, v9, s7
	v_add_u32_e32 v185, s2, v3
	v_mad_u64_u32 v[0:1], s[2:3], v1, s97, v[0:1]
	v_or_b32_e32 v0, v0, v10
	v_lshl_or_b32 v205, s8, 5, v6
	v_add_lshl_u32 v0, v0, v11, 1
	v_mov_b32_e32 v1, v177
	s_mov_b64 s[8:9], 0x160080
	v_lshl_add_u64 v[196:197], v[0:1], 0, s[8:9]
	v_lshrrev_b32_e32 v1, 1, v12
	v_mul_lo_u32 v0, v13, s7
	v_mad_u64_u32 v[0:1], s[2:3], v1, s97, v[0:1]
	s_waitcnt vmcnt(6)
	s_cmp_eq_u64 s[16:17], 0
	v_or_b32_e32 v0, v0, v14
	s_cselect_b64 s[54:55], -1, 0
	s_cmp_lg_u64 s[16:17], 0
	v_add_lshl_u32 v0, v0, v16, 1
	v_mov_b32_e32 v1, v177
	s_mov_b32 s58, 0
	v_lshl_add_u64 v[190:191], v[188:189], 0, 64
	v_lshl_add_u64 v[192:193], v[188:189], 0, s[74:75]
	s_cselect_b64 s[56:57], -1, 0
	v_add_u32_e32 v206, 64, v185
	v_add_u32_e32 v207, 0x80, v185
	v_add_u32_e32 v208, 0xc0, v185
	v_add_u32_e32 v220, 64, v209
	v_add_u32_e32 v221, 0x80, v209
	v_add_u32_e32 v222, 0xc0, v209
	v_lshl_add_u64 v[198:199], v[0:1], 0, s[8:9]
	v_add_u32_e32 v223, 0, v4
	v_add_u32_e32 v224, s6, v2
	s_mov_b32 s60, s94
	s_mov_b32 s62, s90
	s_mov_b64 s[68:69], s[0:1]
	s_barrier
	s_branch .LBB0_1157
	s_nop 0
	s_nop 0
	s_nop 0
	s_nop 0
	s_nop 0
	s_nop 0
	s_nop 0
	s_nop 0
	s_nop 0
	s_nop 0
	s_nop 0
	s_nop 0
	s_nop 0
	s_nop 0
